# dequeue: next queue ticket atomic issued by thread 0 at the start of each unit epilogue (overlaps epilogue), consumed at next dequeue
# baseline (speedup 1.0000x reference)
; DI void attn_phase(const Params& P, char* shm) {
;     ...
;     for (unsigned k = 0; k < 8; ++k) {
;         const unsigned q = (xcd + k) & 7u; unsigned* cnt = P.counter + 16 * q;
.LBB0_316:
	v_writelane_b32 v255, 0, 61
	s_nop 0
	v_readlane_b32 s0, v255, 29
	s_add_i32 s0, s1, s0
	v_writelane_b32 v255, s1, 45
	s_and_b32 s0, s0, 7
	s_lshl_b32 s1, s0, 6
	v_readlane_b32 s2, v255, 25
	s_add_u32 s42, s2, s1
	v_readlane_b32 s1, v255, 26
	s_mul_i32 s41, s0, 0x180
	s_addc_u32 s43, s1, 0
	v_writelane_b32 v255, s41, 46
	v_writelane_b32 v255, s42, 47
	s_nop 1
	v_writelane_b32 v255, s43, 48
	s_branch .LBB0_320

; DI void attn_phase(const Params& P, char* shm) {
;     ...
;             if (tid == 0) su[0] = atomicAdd(cnt, 1u);
.LBB0_320:
	s_and_saveexec_b64 s[0:1], s[34:35]
	s_cbranch_execz .LBB0_324
	v_readlane_b32 s2, v255, 61
	s_cmp_eq_u32 s2, 0
	s_cbranch_scc1 .Ldq_nopf
	s_waitcnt vmcnt(0)
	v_mov_b32_e32 v1, s87
	ds_write_b32 v1, v218
	s_branch .LBB0_324
.Ldq_nopf:
	s_mov_b64 s[6:7], exec
	v_mbcnt_lo_u32_b32 v0, s6, 0
	v_mbcnt_hi_u32_b32 v0, s7, v0
	v_cmp_eq_u32_e32 vcc, 0, v0
	s_and_saveexec_b64 s[4:5], vcc
	s_cbranch_execz .LBB0_323
	s_bcnt1_i32_b64 s2, s[6:7]
	v_mov_b32_e32 v1, s2
	global_atomic_add v1, v2, v1, s[42:43] sc0

; #define ATT_WAIT_BAR() asm volatile("s_waitcnt vmcnt(0) lgkmcnt(0)\n\ts_barrier" ::: "memory")
; DI void attn_phase(const Params& P, char* shm) {
;     ...
;             if (tid == 0) su[0] = atomicAdd(cnt, 1u);
;             ATT_WAIT_BAR();
;             const unsigned ui = su[0];
;             ATT_WAIT_BAR();
;             if (ui >= 384u) break;
;             const unsigned e = P.order[q * 384 + ui]; const int kind = e >> 28, b = (e >> 24) & 15, h = (e >> 16) & 255, qb = e & 0xffff;
.LBB0_324:
	s_or_b64 exec, exec, s[0:1]
	v_writelane_b32 v255, 0, 61
	s_waitcnt lgkmcnt(0)
	s_barrier
	v_mov_b32_e32 v0, s87
	ds_read_b32 v0, v0
	s_waitcnt lgkmcnt(0)
	s_barrier
	s_movk_i32 s0, 0x17f
	s_waitcnt lgkmcnt(0)
	v_cmp_lt_u32_e32 vcc, s0, v0
	s_mov_b64 s[0:1], -1
	s_cbranch_vccnz .LBB0_319
	v_add_u32_e32 v0, s41, v0
	v_mov_b32_e32 v1, v2
	v_lshlrev_b64 v[0:1], 2, v[0:1]
	v_lshl_add_u64 v[0:1], s[22:23], 0, v[0:1]
	global_load_dword v166, v[0:1], off
	s_brev_b32 s1, -16
	s_waitcnt vmcnt(0)
	v_readfirstlane_b32 s0, v166
	v_cmp_lt_u32_e32 vcc, s1, v166
	s_bfe_u32 s2, s0, 0x40018
	s_bfe_u32 s28, s0, 0x80010
	s_and_b32 s3, s0, 0xffff
	s_mov_b64 s[0:1], -1
	s_cbranch_vccz .LBB0_377
	s_brev_b32 s0, -8
	v_cmp_lt_u32_e32 vcc, s0, v166
	s_lshl_b32 s14, s2, 14
	s_lshl_b32 s16, s3, 8
	s_lshl_b32 s15, s28, 6
	s_lshl_b32 s33, s3, 2
	s_mov_b64 s[0:1], -1
	s_mul_i32 s10, s2, 24
	s_cbranch_vccz .LBB0_365
	s_add_i32 s0, s15, 0x400
	v_mov_b32_e32 v53, v236
	s_lshr_b32 s1, s0, 6
	s_add_i32 s1, s1, s10
	v_readfirstlane_b32 s9, v53
	s_ashr_i32 s8, s9, 6
	s_or_b32 s7, s33, 3
	s_lshr_b32 s4, s0, 5
	s_lshl_b32 s0, s1, 21
	s_add_u32 s5, s24, s0
	s_addc_u32 s6, s25, 0
	s_lshl_b32 s0, s8, 9
	s_ashr_i32 s1, s0, 31
	s_lshl_b64 s[0:1], s[0:1], 1
	v_and_b32_e32 v52, 63, v53
	s_add_u32 s0, s5, s0
	s_addc_u32 s1, s6, s1
	v_lshlrev_b32_e32 v0, 4, v52
	v_mov_b32_e32 v1, v2
	v_lshl_add_u64 v[156:157], s[0:1], 0, v[0:1]
	s_mul_i32 s0, s2, 48
	s_add_i32 s0, s4, s0
	s_ashr_i32 s1, s9, 8
	s_add_i32 s0, s0, s1
	s_ashr_i32 s1, s0, 31
	s_lshl_b64 s[0:1], s[0:1], 20
	s_add_u32 s0, s26, s0
	s_addc_u32 s1, s27, s1
	s_lshl_b32 s41, s8, 10
	s_and_b32 s4, s41, 0xc00
	s_add_u32 s0, s0, s4
	s_addc_u32 s1, s1, 0
	s_lshl_b32 s11, s2, 3
	s_add_i32 s11, s11, s28
	s_lshl_b32 s6, s11, 14
	v_lshl_add_u64 v[158:159], s[0:1], 0, v[0:1]
	v_or_b32_e32 v0, s6, v52
	v_readlane_b32 s0, v255, 19
	s_lshl_b32 s20, s7, 13
	v_lshlrev_b32_e32 v0, 4, v0
	v_readlane_b32 s1, v255, 20
	s_cmp_lg_u32 0, -1
	s_nop 0
	v_lshl_add_u64 v[160:161], s[0:1], 0, v[0:1]
	s_cselect_b32 s0, 0, 0
	s_add_i32 s0, s41, s0
	v_lshl_add_u64 v[0:1], v[156:157], 0, s[20:21]
	s_mov_b32 s1, m0
	s_mov_b32 m0, s0
	s_nop 0
	global_load_lds_dwordx4 v[0:1], off
	s_mov_b32 m0, s1
	s_lshl_b32 s20, s7, 12
	s_addk_i32 s0, 0x4000
	s_cmp_lt_u32 s9, 64
	v_lshl_add_u64 v[0:1], v[158:159], 0, s[20:21]
	s_mov_b32 s1, m0
	s_mov_b32 m0, s0
	s_nop 0
	global_load_lds_dwordx4 v[0:1], off
	s_mov_b32 m0, s1
	s_cselect_b64 s[4:5], -1, 0
	s_cmp_gt_u32 s9, 63
	s_cselect_b64 s[0:1], -1, 0
	s_and_b64 vcc, exec, s[0:1]
	s_cbranch_vccnz .LBB0_329
	s_lshl_b32 s20, s7, 10
	s_cmp_lg_u32 0, -1
	s_cselect_b32 s7, 0, 0
	v_lshl_add_u64 v[0:1], v[160:161], 0, s[20:21]
	s_add_i32 s7, s7, 0x8000
	s_mov_b32 s10, m0
	s_mov_b32 m0, s7
	s_nop 0
	global_load_lds_dwordx4 v[0:1], off
	s_mov_b32 m0, s10

; template <int KIND> DI void attn_unit(const Params& P, int b, int h, int qb, char* shm, float lam, bool dry = false) {
;     ...
;     const float rl = __builtin_amdgcn_rcpf(swapsum(lsum));
;     bf16_t* orow = P.Qp + (rowbase + qrow0 + r32) * PITCH + ((KIND == 0) ? h * 128 : qoff);
;     ATT_WAIT_BAR();
;     if (KIND == 0) {
;         LAS float* comb = (LAS float*)shm3 + (size_t)(wid & 3) * 4096 + lane;
;         if (m == 1) {
; #pragma unroll
;             for (int db = 0; db < NDB; ++db)
; #pragma unroll
;                 for (int r = 0; r < 16; ++r) comb[(db * 16 + r) * 64] = o[db][r] * rl;
;         }
;         ATT_WAIT_BAR();
;         if (m == 0) {
;             float ss = 0.f;
; #pragma unroll
;             for (int db = 0; db < NDB; ++db)
; #pragma unroll
;                 for (int r = 0; r < 16; ++r) { const float d = o[db][r] * rl - lam * comb[(db * 16 + r) * 64]; o[db][r] = d; ss += d * d; }
;             ss = swapsum(ss);
;             const float sc = __builtin_amdgcn_rsqf(ss * (1.0f / 128.0f) + RMS_EPS) * (1.0f - P.lam_init);
; #pragma unroll
;             for (int db = 0; db < NDB; ++db)
; #pragma unroll
;                 for (int g = 0; g < 4; g += 2) { u32x2 wp[2];
; #pragma unroll
;                     for (int e = 0; e < 2; ++e) { const f32x4 sg = *(const f32x4*)(P.subg + db * 32 + 8 * (g + e) + 4 * hi); const int r = 4 * (g + e);
;                         wp[e].x = cvtpk(o[db][r] * sc * sg[0], o[db][r + 1] * sc * sg[1]); wp[e].y = cvtpk(o[db][r + 2] * sc * sg[2], o[db][r + 3] * sc * sg[3]); }
;                     store_pair16(orow + db * 32 + 8 * g, hi, wp[0], wp[1], dry); }
;         }
;         ATT_WAIT_BAR();
;     } else {
; #pragma unroll
;         for (int db = 0; db < NDB; ++db)
; #pragma unroll
;             for (int g = 0; g < 4; g += 2) { u32x2 wp[2];
; #pragma unroll
;                 for (int e = 0; e < 2; ++e) { const int r = 4 * (g + e); wp[e].x = cvtpk(o[db][r] * rl, o[db][r + 1] * rl); wp[e].y = cvtpk(o[db][r + 2] * rl, o[db][r + 3] * rl); }
;                 store_pair16(orow + db * 32 + 8 * g, hi, wp[0], wp[1], dry); }
; DI void attn_phase(const Params& P, char* shm) {
;     ...
;         const unsigned q = (xcd + k) & 7u; unsigned* cnt = P.counter + 16 * q;
;         for (;;) {
;             if (tid == 0) su[0] = atomicAdd(cnt, 1u);
;             ATT_WAIT_BAR();
;             const unsigned ui = su[0];
;             ATT_WAIT_BAR();
.LBB0_364:
	v_mov_b32_e32 v0, v169
	s_nop 1
	v_permlane32_swap_b32_e32 v169, v0
	v_add_f32_e32 v0, v169, v0
	v_rcp_f32_e32 v0, v0
	s_waitcnt vmcnt(0) lgkmcnt(0)
	s_barrier
	v_readlane_b32 s100, v255, 47
	v_readlane_b32 s101, v255, 48
	v_readlane_b32 vcc_lo, v255, 39
	v_readlane_b32 vcc_hi, v255, 40
	v_mov_b32_e32 v218, 1
	v_mov_b32_e32 v219, 0
	s_mov_b64 exec, vcc
	s_nop 1
	global_atomic_add v218, v219, v218, s[100:101] sc0
	s_mov_b64 exec, -1
	v_writelane_b32 v255, 1, 61
	s_nop 0
	v_readlane_b32 s96, v255, 32
	v_readlane_b32 s64, v255, 30
	v_pk_mul_f32 v[4:5], v[52:53], v[0:1] op_sel_hi:[1,0]
	v_pk_mul_f32 v[6:7], v[54:55], v[0:1] op_sel_hi:[1,0]
	v_cvt_pk_bf16_f32 v4, v4, v5
	v_cvt_pk_bf16_f32 v5, v6, v7
	v_pk_mul_f32 v[6:7], v[56:57], v[0:1] op_sel_hi:[1,0]
	v_pk_mul_f32 v[8:9], v[58:59], v[0:1] op_sel_hi:[1,0]
	v_cvt_pk_bf16_f32 v6, v6, v7
	v_cvt_pk_bf16_f32 v7, v8, v9
	s_nop 0
	v_permlane32_swap_b32_e32 v4, v6
	v_permlane32_swap_b32_e32 v5, v7
	global_store_dwordx4 v[162:163], v[4:7], off offset:2048
	v_pk_mul_f32 v[8:9], v[66:67], v[0:1] op_sel_hi:[1,0]
	v_readlane_b32 s66, v254, 32
	v_pk_mul_f32 v[4:5], v[60:61], v[0:1] op_sel_hi:[1,0]
	v_pk_mul_f32 v[6:7], v[62:63], v[0:1] op_sel_hi:[1,0]
	v_cvt_pk_bf16_f32 v4, v4, v5
	v_cvt_pk_bf16_f32 v5, v6, v7
	v_pk_mul_f32 v[6:7], v[64:65], v[0:1] op_sel_hi:[1,0]
	v_readlane_b32 s68, v254, 34
	v_cvt_pk_bf16_f32 v6, v6, v7
	v_cvt_pk_bf16_f32 v7, v8, v9
	s_nop 0
	v_permlane32_swap_b32_e32 v4, v6
	v_permlane32_swap_b32_e32 v5, v7
	global_store_dwordx4 v[162:163], v[4:7], off offset:2080
	v_pk_mul_f32 v[8:9], v[42:43], v[0:1] op_sel_hi:[1,0]
	v_readlane_b32 s97, v255, 33
	v_pk_mul_f32 v[4:5], v[36:37], v[0:1] op_sel_hi:[1,0]
	v_pk_mul_f32 v[6:7], v[38:39], v[0:1] op_sel_hi:[1,0]
	v_cvt_pk_bf16_f32 v4, v4, v5
	v_cvt_pk_bf16_f32 v5, v6, v7
	v_pk_mul_f32 v[6:7], v[40:41], v[0:1] op_sel_hi:[1,0]
	v_readlane_b32 s58, v255, 9
	v_cvt_pk_bf16_f32 v6, v6, v7
	v_cvt_pk_bf16_f32 v7, v8, v9
	s_nop 0
	v_permlane32_swap_b32_e32 v4, v6
	v_permlane32_swap_b32_e32 v5, v7
	global_store_dwordx4 v[162:163], v[4:7], off offset:2112
	v_readlane_b32 s52, v255, 11
	v_readlane_b32 s36, v255, 13
	v_pk_mul_f32 v[4:5], v[44:45], v[0:1] op_sel_hi:[1,0]
	v_pk_mul_f32 v[6:7], v[46:47], v[0:1] op_sel_hi:[1,0]
	v_cvt_pk_bf16_f32 v4, v4, v5
	v_cvt_pk_bf16_f32 v5, v6, v7
	v_pk_mul_f32 v[6:7], v[48:49], v[0:1] op_sel_hi:[1,0]
	v_pk_mul_f32 v[0:1], v[50:51], v[0:1] op_sel_hi:[1,0]
	v_cvt_pk_bf16_f32 v6, v6, v7
	v_cvt_pk_bf16_f32 v7, v0, v1
	s_nop 0
	v_permlane32_swap_b32_e32 v4, v6
	v_permlane32_swap_b32_e32 v5, v7
	v_readlane_b32 s24, v255, 15
	v_readlane_b32 s22, v255, 35
	v_readlane_b32 s34, v255, 39
	v_readlane_b32 s42, v255, 47
	global_store_dwordx4 v[162:163], v[4:7], off offset:2144
	s_mov_b64 s[0:1], 0
	v_readlane_b32 s65, v255, 31
	v_readlane_b32 s67, v254, 33
	v_readlane_b32 s69, v254, 35
	v_readlane_b32 s70, v254, 36
	v_readlane_b32 s71, v254, 37
	v_readlane_b32 s72, v254, 38
	v_readlane_b32 s73, v254, 39
	v_readlane_b32 s74, v254, 40
	v_readlane_b32 s75, v254, 41
	v_readlane_b32 s76, v254, 42
	v_readlane_b32 s77, v254, 43
	v_readlane_b32 s78, v254, 44
	v_readlane_b32 s79, v254, 45
	v_readlane_b32 s80, v254, 46
	v_readlane_b32 s81, v254, 47
	v_readlane_b32 s82, v254, 48
	v_readlane_b32 s83, v254, 49
	s_mov_b32 s84, 0xffff0000
	s_mov_b32 s85, 0x43800000
	s_movk_i32 s86, 0xc00
	v_readlane_b32 s87, v254, 50
	s_mov_b32 s88, 0x40c00000
	s_movk_i32 s89, 0x83f
	s_movk_i32 s90, 0x7fff
	s_mov_b32 s91, 0x5400000
	s_mov_b64 s[92:93], 0x1000
	s_mov_b64 s[94:95], 0x200000
	s_mov_b64 s[50:51], 0x80
	s_mov_b64 s[30:31], 0x100
	s_mov_b32 s60, 0x3fb8aa3b
	s_mov_b64 s[62:63], 0x2000
	s_mov_b64 s[54:55], 0x202000
	s_mov_b64 s[56:57], 0x1e0800
	v_readlane_b32 s59, v255, 10
	v_readlane_b32 s53, v255, 12
	v_readlane_b32 s97, v254, 57
	v_readlane_b32 s37, v255, 14
	v_readlane_b32 s25, v255, 16
	v_readlane_b32 s61, v255, 34
	v_readlane_b32 s23, v255, 36
	v_readlane_b32 s26, v255, 37
	v_readlane_b32 s27, v255, 38
	v_readlane_b32 s35, v255, 40
	v_readlane_b32 s29, v255, 41
	v_readlane_b32 s38, v255, 42
	v_readlane_b32 s39, v255, 43
	v_readlane_b32 s40, v255, 44
	v_readlane_b32 s43, v255, 48
	v_readlane_b32 s41, v255, 46
	v_readlane_b32 s3, v255, 49
	v_readlane_b32 s15, v255, 51
	v_readlane_b32 s14, v255, 50
	v_readlane_b32 s16, v255, 52
	s_mul_i32 s10, s2, 24

; #define LAS __attribute__((address_space(3)))
; DI float swapsum(float m) { auto rr = __builtin_amdgcn_permlane32_swap(__float_as_uint(m), __float_as_uint(m), false, false); return __uint_as_float(rr[0]) + __uint_as_float(rr[1]); }
; #define ATT_WAIT_BAR() asm volatile("s_waitcnt vmcnt(0) lgkmcnt(0)\n\ts_barrier" ::: "memory")
; template <int KIND> DI void attn_unit(const Params& P, int b, int h, int qb, char* shm, float lam, bool dry = false) {
;     ...
;     const float rl = __builtin_amdgcn_rcpf(swapsum(lsum));
;     bf16_t* orow = P.Qp + (rowbase + qrow0 + r32) * PITCH + ((KIND == 0) ? h * 128 : qoff);
;     ATT_WAIT_BAR();
;     if (KIND == 0) {
;         LAS float* comb = (LAS float*)shm3 + (size_t)(wid & 3) * 4096 + lane;
;         if (m == 1) {
; #pragma unroll
;             for (int db = 0; db < NDB; ++db)
; #pragma unroll
;                 for (int r = 0; r < 16; ++r) comb[(db * 16 + r) * 64] = o[db][r] * rl;
;         }
;         ATT_WAIT_BAR();
; DI void attn_phase(const Params& P, char* shm) {
;     ...
;         const unsigned q = (xcd + k) & 7u; unsigned* cnt = P.counter + 16 * q;
;         for (;;) {
;             if (tid == 0) su[0] = atomicAdd(cnt, 1u);
;             ATT_WAIT_BAR();
;             const unsigned ui = su[0];
;             ATT_WAIT_BAR();
;             if (ui >= 384u) break;
.LBB0_412:
	v_mov_b32_e32 v4, v197
	s_nop 1
	v_permlane32_swap_b32_e32 v197, v4
	v_add_f32_e32 v4, v197, v4
	v_rcp_f32_e32 v16, v4
	s_waitcnt vmcnt(0) lgkmcnt(0)
	s_barrier
	v_readlane_b32 s100, v255, 47
	v_readlane_b32 s101, v255, 48
	v_readlane_b32 vcc_lo, v255, 39
	v_readlane_b32 vcc_hi, v255, 40
	v_mov_b32_e32 v218, 1
	v_mov_b32_e32 v219, 0
	s_mov_b64 exec, vcc
	s_nop 1
	global_atomic_add v218, v219, v218, s[100:101] sc0
	s_mov_b64 exec, -1
	v_writelane_b32 v255, 1, 61
	s_nop 0
	s_lshl_b32 s0, s9, 14
	s_add_i32 s0, s0, 0
	s_cmp_lg_u32 s8, 1
	v_lshl_add_u32 v4, v195, 2, s0
	s_cbranch_scc1 .LBB0_414
	v_mul_f32_e32 v5, v68, v16
	v_mul_f32_e32 v6, v69, v16
	ds_write2st64_b32 v4, v5, v6 offset1:1
	v_mul_f32_e32 v5, v70, v16
	v_mul_f32_e32 v6, v71, v16
	ds_write2st64_b32 v4, v5, v6 offset0:2 offset1:3
	v_mul_f32_e32 v5, v72, v16
	v_mul_f32_e32 v6, v73, v16
	ds_write2st64_b32 v4, v5, v6 offset0:4 offset1:5
	v_mul_f32_e32 v5, v74, v16
	v_mul_f32_e32 v6, v75, v16
	ds_write2st64_b32 v4, v5, v6 offset0:6 offset1:7
	v_mul_f32_e32 v5, v76, v16
	v_mul_f32_e32 v6, v77, v16
	ds_write2st64_b32 v4, v5, v6 offset0:8 offset1:9
	v_mul_f32_e32 v5, v78, v16
	v_mul_f32_e32 v6, v79, v16
	ds_write2st64_b32 v4, v5, v6 offset0:10 offset1:11
	v_mul_f32_e32 v5, v80, v16
	v_mul_f32_e32 v6, v81, v16
	ds_write2st64_b32 v4, v5, v6 offset0:12 offset1:13
	v_mul_f32_e32 v5, v82, v16
	v_mul_f32_e32 v6, v83, v16
	ds_write2st64_b32 v4, v5, v6 offset0:14 offset1:15
	v_mul_f32_e32 v5, v52, v16
	v_mul_f32_e32 v6, v53, v16
	ds_write2st64_b32 v4, v5, v6 offset0:16 offset1:17
	v_mul_f32_e32 v5, v54, v16
	v_mul_f32_e32 v6, v55, v16
	ds_write2st64_b32 v4, v5, v6 offset0:18 offset1:19
	v_mul_f32_e32 v5, v56, v16
	v_mul_f32_e32 v6, v57, v16
	ds_write2st64_b32 v4, v5, v6 offset0:20 offset1:21
	v_mul_f32_e32 v5, v58, v16
	v_mul_f32_e32 v6, v59, v16
	ds_write2st64_b32 v4, v5, v6 offset0:22 offset1:23
	v_mul_f32_e32 v5, v60, v16
	v_mul_f32_e32 v6, v61, v16
	ds_write2st64_b32 v4, v5, v6 offset0:24 offset1:25
	v_mul_f32_e32 v5, v62, v16
	v_mul_f32_e32 v6, v63, v16
	ds_write2st64_b32 v4, v5, v6 offset0:26 offset1:27
	v_mul_f32_e32 v5, v64, v16
	v_mul_f32_e32 v6, v65, v16
	ds_write2st64_b32 v4, v5, v6 offset0:28 offset1:29
	v_mul_f32_e32 v5, v66, v16
	v_mul_f32_e32 v6, v67, v16
	ds_write2st64_b32 v4, v5, v6 offset0:30 offset1:31
	v_mul_f32_e32 v5, v36, v16
	v_mul_f32_e32 v6, v37, v16
	ds_write2st64_b32 v4, v5, v6 offset0:32 offset1:33
	v_mul_f32_e32 v5, v38, v16
	v_mul_f32_e32 v6, v39, v16
	ds_write2st64_b32 v4, v5, v6 offset0:34 offset1:35
	v_mul_f32_e32 v5, v40, v16
	v_mul_f32_e32 v6, v41, v16
	ds_write2st64_b32 v4, v5, v6 offset0:36 offset1:37
	v_mul_f32_e32 v5, v42, v16
	v_mul_f32_e32 v6, v43, v16
	ds_write2st64_b32 v4, v5, v6 offset0:38 offset1:39
	v_mul_f32_e32 v5, v44, v16
	v_mul_f32_e32 v6, v45, v16
	ds_write2st64_b32 v4, v5, v6 offset0:40 offset1:41
	v_mul_f32_e32 v5, v46, v16
	v_mul_f32_e32 v6, v47, v16
	ds_write2st64_b32 v4, v5, v6 offset0:42 offset1:43
	v_mul_f32_e32 v5, v48, v16
	v_mul_f32_e32 v6, v49, v16
	ds_write2st64_b32 v4, v5, v6 offset0:44 offset1:45
	v_mul_f32_e32 v5, v50, v16
	v_mul_f32_e32 v6, v51, v16
	ds_write2st64_b32 v4, v5, v6 offset0:46 offset1:47
	v_mul_f32_e32 v5, v20, v16
	v_mul_f32_e32 v6, v21, v16
	ds_write2st64_b32 v4, v5, v6 offset0:48 offset1:49
	v_mul_f32_e32 v5, v22, v16
	v_mul_f32_e32 v6, v23, v16
	ds_write2st64_b32 v4, v5, v6 offset0:50 offset1:51
	v_mul_f32_e32 v5, v24, v16
	v_mul_f32_e32 v6, v25, v16
	ds_write2st64_b32 v4, v5, v6 offset0:52 offset1:53
	v_mul_f32_e32 v5, v26, v16
	v_mul_f32_e32 v6, v27, v16
	ds_write2st64_b32 v4, v5, v6 offset0:54 offset1:55
	v_mul_f32_e32 v5, v28, v16
	v_mul_f32_e32 v6, v29, v16
	ds_write2st64_b32 v4, v5, v6 offset0:56 offset1:57
	v_mul_f32_e32 v5, v30, v16
	v_mul_f32_e32 v6, v31, v16
	ds_write2st64_b32 v4, v5, v6 offset0:58 offset1:59
	v_mul_f32_e32 v5, v32, v16
	v_mul_f32_e32 v6, v33, v16
	ds_write2st64_b32 v4, v5, v6 offset0:60 offset1:61
	v_mul_f32_e32 v5, v34, v16
	v_mul_f32_e32 v6, v35, v16
	ds_write2st64_b32 v4, v5, v6 offset0:62 offset1:63

; template <int KIND> DI void attn_unit(const Params& P, int b, int h, int qb, char* shm, float lam, bool dry = false) {
;     ...
;     const float rl = __builtin_amdgcn_rcpf(swapsum(lsum));
;     bf16_t* orow = P.Qp + (rowbase + qrow0 + r32) * PITCH + ((KIND == 0) ? h * 128 : qoff);
;     ATT_WAIT_BAR();
;     if (KIND == 0) {
;         LAS float* comb = (LAS float*)shm3 + (size_t)(wid & 3) * 4096 + lane;
;         if (m == 1) {
; #pragma unroll
;             for (int db = 0; db < NDB; ++db)
; #pragma unroll
;                 for (int r = 0; r < 16; ++r) comb[(db * 16 + r) * 64] = o[db][r] * rl;
;         }
;         ATT_WAIT_BAR();
;         if (m == 0) {
;             float ss = 0.f;
; #pragma unroll
;             for (int db = 0; db < NDB; ++db)
; #pragma unroll
;                 for (int r = 0; r < 16; ++r) { const float d = o[db][r] * rl - lam * comb[(db * 16 + r) * 64]; o[db][r] = d; ss += d * d; }
;             ss = swapsum(ss);
;             const float sc = __builtin_amdgcn_rsqf(ss * (1.0f / 128.0f) + RMS_EPS) * (1.0f - P.lam_init);
; #pragma unroll
;             for (int db = 0; db < NDB; ++db)
; #pragma unroll
;                 for (int g = 0; g < 4; g += 2) { u32x2 wp[2];
; #pragma unroll
;                     for (int e = 0; e < 2; ++e) { const f32x4 sg = *(const f32x4*)(P.subg + db * 32 + 8 * (g + e) + 4 * hi); const int r = 4 * (g + e);
;                         wp[e].x = cvtpk(o[db][r] * sc * sg[0], o[db][r + 1] * sc * sg[1]); wp[e].y = cvtpk(o[db][r + 2] * sc * sg[2], o[db][r + 3] * sc * sg[3]); }
;                     store_pair16(orow + db * 32 + 8 * g, hi, wp[0], wp[1], dry); }
;         }
;         ATT_WAIT_BAR();
;     } else {
; #pragma unroll
;         for (int db = 0; db < NDB; ++db)
; #pragma unroll
;             for (int g = 0; g < 4; g += 2) { u32x2 wp[2];
; #pragma unroll
;                 for (int e = 0; e < 2; ++e) { const int r = 4 * (g + e); wp[e].x = cvtpk(o[db][r] * rl, o[db][r + 1] * rl); wp[e].y = cvtpk(o[db][r + 2] * rl, o[db][r + 3] * rl); }
;                 store_pair16(orow + db * 32 + 8 * g, hi, wp[0], wp[1], dry); }
; DI void attn_phase(const Params& P, char* shm) {
;     ...
;         const unsigned q = (xcd + k) & 7u; unsigned* cnt = P.counter + 16 * q;
;         for (;;) {
;             if (tid == 0) su[0] = atomicAdd(cnt, 1u);
;             ATT_WAIT_BAR();
;             const unsigned ui = su[0];
;             ATT_WAIT_BAR();
.LBB0_437:
	v_mov_b32_e32 v0, v159
	s_nop 1
	v_permlane32_swap_b32_e32 v159, v0
	v_add_f32_e32 v0, v159, v0
	v_rcp_f32_e32 v0, v0
	s_waitcnt vmcnt(0) lgkmcnt(0)
	s_barrier
	v_readlane_b32 s100, v255, 47
	v_readlane_b32 s101, v255, 48
	v_readlane_b32 vcc_lo, v255, 39
	v_readlane_b32 vcc_hi, v255, 40
	v_mov_b32_e32 v218, 1
	v_mov_b32_e32 v219, 0
	s_mov_b64 exec, vcc
	s_nop 1
	global_atomic_add v218, v219, v218, s[100:101] sc0
	s_mov_b64 exec, -1
	v_writelane_b32 v255, 1, 61
	s_nop 0
	s_nop 0
	v_pk_mul_f32 v[4:5], v[4:5], v[0:1] op_sel_hi:[1,0]
	v_pk_mul_f32 v[6:7], v[6:7], v[0:1] op_sel_hi:[1,0]
	v_cvt_pk_bf16_f32 v4, v4, v5
	v_cvt_pk_bf16_f32 v5, v6, v7
	v_pk_mul_f32 v[6:7], v[8:9], v[0:1] op_sel_hi:[1,0]
	v_pk_mul_f32 v[8:9], v[10:11], v[0:1] op_sel_hi:[1,0]
	v_cvt_pk_bf16_f32 v6, v6, v7
	v_cvt_pk_bf16_f32 v7, v8, v9
	s_nop 0
	v_permlane32_swap_b32_e32 v4, v6
	v_permlane32_swap_b32_e32 v5, v7
	global_store_dwordx4 v[152:153], v[4:7], off offset:1024
	v_pk_mul_f32 v[8:9], v[18:19], v[0:1] op_sel_hi:[1,0]
	s_nop 0
	v_pk_mul_f32 v[4:5], v[12:13], v[0:1] op_sel_hi:[1,0]
	v_pk_mul_f32 v[6:7], v[14:15], v[0:1] op_sel_hi:[1,0]
	v_cvt_pk_bf16_f32 v4, v4, v5
	v_cvt_pk_bf16_f32 v5, v6, v7
	v_pk_mul_f32 v[6:7], v[16:17], v[0:1] op_sel_hi:[1,0]
	s_nop 0
	v_cvt_pk_bf16_f32 v6, v6, v7
	v_cvt_pk_bf16_f32 v7, v8, v9
	s_nop 0
	v_permlane32_swap_b32_e32 v4, v6
	v_permlane32_swap_b32_e32 v5, v7
	global_store_dwordx4 v[152:153], v[4:7], off offset:1056
	v_pk_mul_f32 v[8:9], v[26:27], v[0:1] op_sel_hi:[1,0]
	s_nop 0
	v_pk_mul_f32 v[4:5], v[20:21], v[0:1] op_sel_hi:[1,0]
	v_pk_mul_f32 v[6:7], v[22:23], v[0:1] op_sel_hi:[1,0]
	v_cvt_pk_bf16_f32 v4, v4, v5
	v_cvt_pk_bf16_f32 v5, v6, v7
	v_pk_mul_f32 v[6:7], v[24:25], v[0:1] op_sel_hi:[1,0]
	s_nop 0
	v_cvt_pk_bf16_f32 v6, v6, v7
	v_cvt_pk_bf16_f32 v7, v8, v9
	s_nop 0
	v_permlane32_swap_b32_e32 v4, v6
	v_permlane32_swap_b32_e32 v5, v7
	global_store_dwordx4 v[152:153], v[4:7], off offset:1088
	s_nop 1
	v_pk_mul_f32 v[4:5], v[28:29], v[0:1] op_sel_hi:[1,0]
	v_pk_mul_f32 v[6:7], v[30:31], v[0:1] op_sel_hi:[1,0]
	v_cvt_pk_bf16_f32 v4, v4, v5
	v_cvt_pk_bf16_f32 v5, v6, v7
	v_pk_mul_f32 v[6:7], v[32:33], v[0:1] op_sel_hi:[1,0]
	v_pk_mul_f32 v[0:1], v[34:35], v[0:1] op_sel_hi:[1,0]
	v_cvt_pk_bf16_f32 v6, v6, v7
	v_cvt_pk_bf16_f32 v7, v0, v1
	s_nop 0
	v_permlane32_swap_b32_e32 v4, v6
	v_permlane32_swap_b32_e32 v5, v7
	global_store_dwordx4 v[152:153], v[4:7], off offset:1120
	s_cbranch_execnz .LBB0_318
	s_branch .LBB0_378

; __global__ void __launch_bounds__(NWAVES * 64, 2) fwd_kernel(Args a) {
	.amdhsa_kernel _Z10fwd_kernel4Args
		.amdhsa_group_segment_fixed_size 0
		.amdhsa_private_segment_fixed_size 0
		.amdhsa_kernarg_size 408
		.amdhsa_user_sgpr_count 2
		.amdhsa_user_sgpr_dispatch_ptr 0
		.amdhsa_user_sgpr_queue_ptr 0
		.amdhsa_user_sgpr_kernarg_segment_ptr 1
		.amdhsa_user_sgpr_dispatch_id 0
		.amdhsa_user_sgpr_kernarg_preload_length 0
		.amdhsa_user_sgpr_kernarg_preload_offset 0
		.amdhsa_user_sgpr_private_segment_size 0
		.amdhsa_uses_dynamic_stack 0
		.amdhsa_enable_private_segment 0
		.amdhsa_system_sgpr_workgroup_id_x 1
		.amdhsa_system_sgpr_workgroup_id_y 0
		.amdhsa_system_sgpr_workgroup_id_z 0
		.amdhsa_system_sgpr_workgroup_info 0
		.amdhsa_system_vgpr_workitem_id 2
		.amdhsa_next_free_vgpr 256
		.amdhsa_next_free_sgpr 102
		.amdhsa_accum_offset 256
		.amdhsa_reserve_vcc 1
		.amdhsa_float_round_mode_32 0
		.amdhsa_float_round_mode_16_64 0
		.amdhsa_float_denorm_mode_32 3
		.amdhsa_float_denorm_mode_16_64 3
		.amdhsa_dx10_clamp 1
		.amdhsa_ieee_mode 1
		.amdhsa_fp16_overflow 0
		.amdhsa_tg_split 0
		.amdhsa_exception_fp_ieee_invalid_op 0
		.amdhsa_exception_fp_denorm_src 0
		.amdhsa_exception_fp_ieee_div_zero 0
		.amdhsa_exception_fp_ieee_overflow 0
		.amdhsa_exception_fp_ieee_underflow 0
		.amdhsa_exception_fp_ieee_inexact 0
		.amdhsa_exception_int_div_zero 0
	.end_amdhsa_kernel

; __global__ void __launch_bounds__(NWAVES * 64, 2) fwd_kernel(Args a) {
amdhsa.kernels:
  - .agpr_count:     0
    .args:
      - .offset:         0
        .size:           152
        .value_kind:     by_value
      - .offset:         152
        .size:           4
        .value_kind:     hidden_block_count_x
      - .offset:         156
        .size:           4
        .value_kind:     hidden_block_count_y
      - .offset:         160
        .size:           4
        .value_kind:     hidden_block_count_z
      - .offset:         164
        .size:           2
        .value_kind:     hidden_group_size_x
      - .offset:         166
        .size:           2
        .value_kind:     hidden_group_size_y
      - .offset:         168
        .size:           2
        .value_kind:     hidden_group_size_z
      - .offset:         170
        .size:           2
        .value_kind:     hidden_remainder_x
      - .offset:         172
        .size:           2
        .value_kind:     hidden_remainder_y
      - .offset:         174
        .size:           2
        .value_kind:     hidden_remainder_z
      - .offset:         192
        .size:           8
        .value_kind:     hidden_global_offset_x
      - .offset:         200
        .size:           8
        .value_kind:     hidden_global_offset_y
      - .offset:         208
        .size:           8
        .value_kind:     hidden_global_offset_z
      - .offset:         216
        .size:           2
        .value_kind:     hidden_grid_dims
      - .offset:         240
        .size:           8
        .value_kind:     hidden_multigrid_sync_arg
      - .offset:         272
        .size:           4
        .value_kind:     hidden_dynamic_lds_size
    .group_segment_fixed_size: 0
    .kernarg_segment_align: 8
    .kernarg_segment_size: 408
    .language:       OpenCL C
    .language_version:
      - 2
      - 0
    .max_flat_workgroup_size: 512
    .name:           _Z10fwd_kernel4Args
    .private_segment_fixed_size: 0
    .sgpr_count:     108
    .sgpr_spill_count: 253
    .symbol:         _Z10fwd_kernel4Args.kd
    .uniform_work_group_size: 1
    .uses_dynamic_stack: false
    .vgpr_count:     256
    .vgpr_spill_count: 0
    .wavefront_size: 64
